# v33 + next-iteration K/V tile loads issued inside the fused block (first attention unit), header loads skipped via flag
# speedup vs baseline: 1.0030x; 1.0023x over previous
; #define ATT_LOADK(t) do { const bf16_t* kp_ = kbase + (size_t)(64 * (t)) * 768 + kgo; _Pragma("unroll") for (int i = 0; i < 3; ++i) kreg[i] = *(const u32x4*)(kp_ + 64 * i); } while (0)
; #define ATT_LOADV(t) do { const bf16_t* vp_ = vbase + 64 * (t) + vgo; _Pragma("unroll") for (int i = 0; i < 2; ++i) vreg[i] = *(const u32x4*)(vp_ + 32 * i); } while (0)
; DI void attn_unit(LAS unsigned char* lds, const bf16_t* __restrict__ Q, const bf16_t* __restrict__ Kg, const bf16_t* __restrict__ VT, bf16_t* __restrict__ MIX, int b, int h, int c0, int nq, int desc) {
;     ...
;   for (int t = 0; t < nt; ++t) {
;     const int buf = t & 1; const int tau = TAU(t), taun = TAU(t + 1);
;     if (t + 2 < nt) ATT_LOADK(TAU(t + 2));
;     if (t + 1 < nt) ATT_LOADV(taun);
;     const bool do_cur = active && tau <= cq; const bool do_next = active && (taun <= cq) && (t + 1 < nt);
.LBB0_539:
	s_add_i32 s12, s23, 0x103
	s_cmp_lt_i32 s12, s17
	s_cselect_b64 s[26:27], -1, 0
	s_cmp_ge_i32 s12, s17
	s_cbranch_scc1 .LBB0_541
	s_add_i32 s98, s23, 131072
	s_cmp_eq_u32 s98, s99
	s_cbranch_scc1 .LBB0_541
	v_mad_u64_u32 v[98:99], s[28:29], s68, v227, v[200:201]
	s_waitcnt vmcnt(0)
	global_load_dwordx4 v[178:181], v[98:99], off
	global_load_dwordx4 v[182:185], v[98:99], off offset:128
	global_load_dwordx4 v[186:189], v[98:99], off offset:256
.LBB0_541:
	s_add_i32 s12, s23, 0x102
	s_cmp_lt_i32 s12, s17
	s_cselect_b64 s[28:29], -1, 0
	s_cmp_ge_i32 s12, s17
	s_cbranch_scc1 .LBB0_543
	s_add_i32 s98, s23, 131072
	s_cmp_eq_u32 s98, s99
	s_cbranch_scc1 .LBB0_543
	s_sub_i32 s12, s68, 64
	v_lshl_add_u64 v[98:99], s[12:13], 1, v[202:203]
	global_load_dwordx4 v[190:193], v[98:99], off
	global_load_dwordx4 v[194:197], v[98:99], off offset:64

; #define LAS __attribute__((address_space(3)))
; #define MFMA32(a, b, c) __builtin_amdgcn_mfma_f32_32x32x16_bf16((a), (b), (c), 0, 0, 0)
; DI bf16x8 pack8(const f32x16& x, int s) { u32x4 p; p.x = pk2(x[8 * s], x[8 * s + 1]); p.y = pk2(x[8 * s + 2], x[8 * s + 3]); p.z = pk2(x[8 * s + 4], x[8 * s + 5]); p.w = pk2(x[8 * s + 6], x[8 * s + 7]); return __builtin_bit_cast(bf16x8, p); }
; DI void attn_unit(LAS unsigned char* lds, const bf16_t* __restrict__ Q, const bf16_t* __restrict__ Kg, const bf16_t* __restrict__ VT, bf16_t* __restrict__ MIX, int b, int h, int c0, int nq, int desc) {
;     ...
;       __builtin_amdgcn_sched_barrier(0);
; #pragma unroll
;       for (int sx = 0; sx < 12; ++sx) { const bf16x8 a0 = *(const LAS bf16x8*)(kb2 + 32 * sx); const bf16x8 a1 = *(const LAS bf16x8*)(kb2 + 32 * KROWB + 32 * sx);
;         n0 = MFMA32(a0, qf[sx], n0); n1 = MFMA32(a1, qf[sx], n1);
; #pragma unroll
;         for (int j = 0; j < 3; ++j) { const int ei = 3 * sx + j; if (ei < 16) s0[ei] = __builtin_amdgcn_exp2f(s0[ei] - mrun); else if (ei < 32) s1[ei - 16] = __builtin_amdgcn_exp2f(s1[ei - 16] - mrun); }
;         __builtin_amdgcn_sched_barrier(0); }
;       float ps = 0.f;
; #pragma unroll
;       for (int i = 0; i < 16; ++i) ps += s0[i] + s1[i];
;       lrun += ps;
;       bf16x8 pf[4]; pf[0] = pack8(s0, 0); pf[1] = pack8(s0, 1); pf[2] = pack8(s1, 0); pf[3] = pack8(s1, 1);
;       const LAS unsigned char* vb = lds + 2 * ATT_KB + buf * ATT_VB + r31 * HROW + 16 * hh;
; #pragma unroll
;       for (int kk = 0; kk < 4; ++kk)
; #pragma unroll
;         for (int d = 0; d < 4; ++d) { const bf16x8 a = *(const LAS bf16x8*)(vb + d * 32 * HROW + 32 * kk); O[d] = MFMA32(a, pf[kk], O[d]); }
.Lnok_LBB0_551:
	s_waitcnt lgkmcnt(3)
	v_mfma_f32_32x32x16_bf16 v[2:17], v[234:237], v[82:85], v[2:17]
	ds_read_b128 v[234:237], v223 offset:65056
	v_add_f32_e32 v238, v238, v239
	v_add_f32_e32 v240, v240, v241
	v_mov_b64_e32 v[86:87], v[102:103]
	v_mov_b64_e32 v[94:95], v[110:111]
	s_waitcnt lgkmcnt(3)
	v_mfma_f32_32x32x16_bf16 v[50:65], v[212:215], v[90:93], v[50:65]
	ds_read_b128 v[212:215], v223 offset:51264
	v_add_f32_e32 v0, v238, v240
	v_mov_b64_e32 v[70:71], v[118:119]
	v_mov_b64_e32 v[78:79], v[126:127]
	s_waitcnt lgkmcnt(3)
	v_mfma_f32_32x32x16_bf16 v[34:49], v[218:221], v[90:93], v[34:49]
	ds_read_b128 v[218:221], v223 offset:55872
	v_add_f32_e32 v210, v210, v0
	v_mov_b64_e32 v[88:89], v[104:105]
	v_mov_b64_e32 v[96:97], v[112:113]
	s_waitcnt lgkmcnt(3)
	v_mfma_f32_32x32x16_bf16 v[18:33], v[230:233], v[90:93], v[18:33]
	ds_read_b128 v[230:233], v223 offset:60480
	s_xor_b32 s98, s12, 1
	s_mulk_i32 s98, 0x4800
	v_add_u32_e32 v229, s98, v206
	s_waitcnt vmcnt(0)
	ds_write_b128 v229, v[190:193] offset:51200
	ds_write_b128 v229, v[194:197] offset:51264
	v_max3_f32 v239, v98, v99, v100
	v_max3_f32 v241, v101, v102, v103
	s_waitcnt lgkmcnt(3)
	v_mfma_f32_32x32x16_bf16 v[2:17], v[234:237], v[90:93], v[2:17]
	ds_read_b128 v[234:237], v223 offset:65088
	v_max3_f32 v239, v239, v104, v105
	v_max3_f32 v241, v241, v106, v107
	v_mov_b64_e32 v[72:73], v[120:121]
	v_mov_b64_e32 v[80:81], v[128:129]
	s_waitcnt lgkmcnt(3)
	v_mfma_f32_32x32x16_bf16 v[50:65], v[212:215], v[66:69], v[50:65]
	ds_read_b128 v[212:215], v223 offset:51296
	v_max3_f32 v239, v239, v108, v109
	v_max3_f32 v241, v241, v110, v111
	v_mov_b64_e32 v[82:83], v[98:99]
	v_mov_b64_e32 v[84:85], v[100:101]
	s_waitcnt lgkmcnt(3)
	v_mfma_f32_32x32x16_bf16 v[34:49], v[218:221], v[66:69], v[34:49]
	ds_read_b128 v[218:221], v223 offset:55904
	v_max3_f32 v239, v239, v112, v113
	v_max3_f32 v241, v241, v114, v115
	s_add_i32 s98, s23, 0x104
	s_cmp_lt_i32 s98, s17
	s_cbranch_scc0 .Lnk_LBB0_551
	s_add_i32 s98, s68, 64
	v_mad_u64_u32 v[242:243], vcc, s98, v227, v[200:201]
	global_load_dwordx4 v[178:181], v[242:243], off
	global_load_dwordx4 v[182:185], v[242:243], off offset:128
	global_load_dwordx4 v[186:189], v[242:243], off offset:256
.Lnk_LBB0_551:
	v_mov_b64_e32 v[90:91], v[106:107]
	v_mov_b64_e32 v[92:93], v[108:109]
	s_waitcnt lgkmcnt(3)
	v_mfma_f32_32x32x16_bf16 v[18:33], v[230:233], v[66:69], v[18:33]
	ds_read_b128 v[230:233], v223 offset:60512
	v_max3_f32 v239, v239, v116, v117
	v_max3_f32 v241, v241, v118, v119
	s_waitcnt lgkmcnt(3)
	v_mfma_f32_32x32x16_bf16 v[2:17], v[234:237], v[66:69], v[2:17]
	ds_read_b128 v[234:237], v223 offset:65120
	v_max3_f32 v239, v239, v120, v121
	v_max3_f32 v241, v241, v122, v123
	s_add_i32 s98, s23, 0x103
	s_cmp_lt_i32 s98, s17
	s_cbranch_scc0 .Lnv_LBB0_551
	s_mov_b32 s100, s68
	s_mov_b32 s101, 0
	v_lshl_add_u64 v[242:243], s[100:101], 1, v[202:203]
	global_load_dwordx4 v[190:193], v[242:243], off
	global_load_dwordx4 v[194:197], v[242:243], off offset:64
.Lnv_LBB0_551:
	s_waitcnt lgkmcnt(3)
	v_mfma_f32_32x32x16_bf16 v[50:65], v[212:215], v[74:77], v[50:65]
	v_max3_f32 v239, v239, v124, v125
	v_max3_f32 v241, v241, v126, v127
	v_mov_b64_e32 v[66:67], v[114:115]
	v_mov_b64_e32 v[68:69], v[116:117]
	s_waitcnt lgkmcnt(2)
	v_mfma_f32_32x32x16_bf16 v[34:49], v[218:221], v[74:77], v[34:49]
	v_max3_f32 v239, v239, v128, v129
	v_max_f32_e32 v241, v239, v241
	s_waitcnt lgkmcnt(1)
	v_mfma_f32_32x32x16_bf16 v[18:33], v[230:233], v[74:77], v[18:33]
	s_waitcnt lgkmcnt(0)
	v_mfma_f32_32x32x16_bf16 v[2:17], v[234:237], v[74:77], v[2:17]
	v_mov_b32_e32 v239, v241
	s_nop 1
	v_permlane32_swap_b32_e32 v241, v239
	v_max_f32_e32 v241, v241, v239
	v_mov_b64_e32 v[74:75], v[122:123]
	v_mov_b64_e32 v[76:77], v[124:125]
	s_add_i32 s99, s23, 131073
	s_or_b64 exec, exec, s[30:31]
	s_branch .LBB0_554
	s_andn2_b64 vcc, exec, s[26:27]
	s_cbranch_vccz .LBB0_560

; #define ATT_LOADK(t) do { const bf16_t* kp_ = kbase + (size_t)(64 * (t)) * 768 + kgo; _Pragma("unroll") for (int i = 0; i < 3; ++i) kreg[i] = *(const u32x4*)(kp_ + 64 * i); } while (0)
; #define ATT_LOADV(t) do { const bf16_t* vp_ = vbase + 64 * (t) + vgo; _Pragma("unroll") for (int i = 0; i < 2; ++i) vreg[i] = *(const u32x4*)(vp_ + 32 * i); } while (0)
; DI void attn_unit(LAS unsigned char* lds, const bf16_t* __restrict__ Q, const bf16_t* __restrict__ Kg, const bf16_t* __restrict__ VT, bf16_t* __restrict__ MIX, int b, int h, int c0, int nq, int desc) {
;     ...
;   for (int t = 0; t < nt; ++t) {
;     const int buf = t & 1; const int tau = TAU(t), taun = TAU(t + 1);
;     if (t + 2 < nt) ATT_LOADK(TAU(t + 2));
;     if (t + 1 < nt) ATT_LOADV(taun);
;     const bool do_cur = active && tau <= cq; const bool do_next = active && (taun <= cq) && (t + 1 < nt);
.LBB0_2550:
	s_add_i32 s0, s23, 0x103
	s_cmp_lt_i32 s0, s17
	s_cselect_b64 s[26:27], -1, 0
	s_cmp_ge_i32 s0, s17
	s_cbranch_scc1 .LBB0_2552
	s_add_i32 s98, s23, 131072
	s_cmp_eq_u32 s98, s99
	s_cbranch_scc1 .LBB0_2552
	v_mad_u64_u32 v[98:99], s[28:29], s68, v227, v[200:201]
	s_waitcnt vmcnt(0)
	global_load_dwordx4 v[178:181], v[98:99], off
	global_load_dwordx4 v[182:185], v[98:99], off offset:128
	global_load_dwordx4 v[186:189], v[98:99], off offset:256
.LBB0_2552:
	s_add_i32 s0, s23, 0x102
	s_cmp_lt_i32 s0, s17
	s_cselect_b64 s[28:29], -1, 0
	s_cmp_ge_i32 s0, s17
	s_cbranch_scc1 .LBB0_2554
	s_add_i32 s98, s23, 131072
	s_cmp_eq_u32 s98, s99
	s_cbranch_scc1 .LBB0_2554
	s_sub_i32 s12, s68, 64
	v_lshl_add_u64 v[98:99], s[12:13], 1, v[202:203]
	global_load_dwordx4 v[190:193], v[98:99], off
	global_load_dwordx4 v[194:197], v[98:99], off offset:64
